# P3 load balance: v^T GEMM tiles reassigned to workgroups 128-255 (two each) since workgroups 0-127 carry two q tiles; same tiles, same math
# speedup vs baseline: 1.0054x; 1.0054x over previous
; #define PH(n) if constexpr ((PHASE_MASK >> (n)) & 1)
; __device__ __forceinline__ bool tile_order(long L, int nM, int nN, int& pm, int& pn) {
;     const int nwg = nM * nN; if (L >= nwg) return false;
;     int wgid = (int)L; { const int q = nwg / NXCD, r = nwg % NXCD, xcd = wgid % NXCD, off = wgid / NXCD; wgid = (xcd < r ? xcd * (q + 1) : r * (q + 1) + (xcd - r) * q) + off; }
;     const int nig = WGM * nN, gid = wgid / nig, fm = gid * WGM, gsz = (nM - fm) < WGM ? (nM - fm) : WGM;
;     pm = fm + ((wgid % nig) % gsz); pn = (wgid % nig) / gsz; return true;
; __global__ void __launch_bounds__(512, 2) fwd_mega(Args a) {
;     ...
;         PH(10) {
;             pg8::Gemm g{Wv_t, CKVN, 128, 128, 128}; pg8::SchedPlain S{2, TOK / 256, G, bx, (size_t)256 * 128 * 2, (size_t)256 * 128 * 2};
;             pg8::Epi8<FVt> E{FVt{Vt}};
;             pg8::gemm_phase(lds, g, S, E, wave);
;         }
.LBB0_780:
	v_mov_b32_e32 v8, v184
	s_and_b64 vcc, exec, s[4:5]
	s_cbranch_vccnz .LBB0_805
	s_cmpk_lt_i32 s2, 0x80
	s_cbranch_scc1 .LBB0_805
	s_addk_i32 s2, 0xff80
	s_movk_i32 s18, 0x80
	s_ashr_i32 s24, s2, 31
	s_lshr_b32 s6, s24, 29
	s_add_i32 s9, s2, s6
	s_and_b32 s6, s9, -8
	s_sub_i32 s10, s2, s6
	s_cmp_gt_i32 s10, -1
	s_cbranch_scc0 .LBB0_783
	s_lshl_b32 s8, s10, 5
	s_cbranch_execz .LBB0_784
	s_branch .LBB0_785

; #define PG8_WAIT_V(n) asm volatile("s_waitcnt vmcnt(" #n ")" ::: "memory")
; #define PG8_BAR __builtin_amdgcn_s_barrier()
; template <class Epi, class Sched>
; __device__ __forceinline__ void gemm_phase(LAS unsigned char* lds, const Gemm g, const Sched& S, const Epi& E, const int wave_) {
;     ...
;     PG8_WAIT_V(0);
;     PG8_BAR;
.LBB0_804:
	s_addk_i32 s2, 0x80
	s_movk_i32 s18, 0x100
	s_waitcnt vmcnt(0)
	s_barrier
